# P6 h1 tile init loads marked nt (once-read stream); otherwise as previous
# baseline (speedup 1.0000x reference)
.LBB0_470:
	s_waitcnt vmcnt(0)
	v_lshlrev_b32_e32 v0, 4, v168
	s_waitcnt lgkmcnt(0)
	v_and_b32_e32 v1, 32, v168
	v_bfe_u32 v132, v168, 2, 4
	v_lshrrev_b32_e32 v2, 3, v168
	s_movk_i32 s5, 0x70
	v_add_u32_e32 v136, 0x2000, v0
	s_add_u32 s50, s30, 0x6200000
	v_bitop3_b32 v134, v0, v1, 48 bitop3:0x6c
	v_and_or_b32 v2, v2, s5, v132
	v_lshrrev_b32_e32 v0, 7, v136
	s_movk_i32 s5, 0xf0
	s_addc_u32 s51, s31, 0
	v_and_or_b32 v0, v0, s5, v132
	s_lshl_b32 s5, s18, 4
	s_and_b32 s52, s5, 0xfffffc00
	s_lshr_b32 s5, s18, 1
	s_add_i32 s4, s6, s4
	s_and_b32 s20, s5, 0x60
	s_ashr_i32 s5, s4, 31
	s_lshr_b32 s5, s5, 28
	s_add_i32 s5, s4, s5
	s_ashr_i32 s6, s5, 4
	s_and_b32 s5, s5, 0xfff0
	s_sub_i32 s4, s4, s5
	s_bfe_u32 s5, s4, 0x10007
	s_add_i32 s5, s4, s5
	s_bfe_i32 s7, s5, 0x80000
	s_and_b32 s5, s5, 0xfe
	s_sub_i32 s4, s4, s5
	s_lshl_b32 s6, s6, 1
	s_sext_i32_i8 s4, s4
	s_lshr_b32 s16, s18, 8
	s_add_i32 s36, s6, s4
	v_and_b32_e32 v135, 64, v168
	s_lshl_b32 s19, s16, 6
	s_sext_i32_i16 s7, s7
	s_lshl_b32 s4, s36, 8
	v_or_b32_e32 v1, v134, v135
	v_and_b32_e32 v133, 15, v168
	s_ashr_i32 s77, s7, 1
	s_add_i32 s4, s4, s19
	v_lshl_or_b32 v130, v0, 14, v1
	v_bfe_u32 v137, v168, 4, 2
	v_or_b32_e32 v0, s4, v133
	s_lshl_b32 s4, s77, 8
	s_ashr_i32 s14, s36, 3
	s_or_b32 s4, s4, s20
	v_lshlrev_b32_e32 v138, 2, v137
	s_ashr_i32 s15, s14, 31
	v_lshl_or_b32 v128, v2, 14, v1
	s_lshr_b32 s12, s7, 1
	v_or_b32_e32 v2, s4, v138
	s_lshl_b64 s[4:5], s[14:15], 25
	s_add_u32 s4, s62, s4
	v_or_b32_e32 v12, 16, v0
	s_addc_u32 s5, s63, s5
	v_ashrrev_i32_e32 v3, 31, v2
	v_ashrrev_i32_e32 v1, 31, v0
	v_ashrrev_i32_e32 v13, 31, v12
	v_lshl_add_u64 v[4:5], v[2:3], 1, s[4:5]
	v_lshlrev_b64 v[2:3], 12, v[0:1]
	v_lshlrev_b64 v[12:13], 12, v[12:13]
	v_lshl_add_u64 v[16:17], v[4:5], 0, v[2:3]
	v_lshl_add_u64 v[18:19], v[4:5], 0, v[12:13]
	global_load_dwordx2 v[2:3], v[16:17], off nt
	global_load_dwordx2 v[6:7], v[16:17], off offset:32 nt
	global_load_dwordx2 v[10:11], v[16:17], off offset:256 nt
	global_load_dwordx2 v[8:9], v[16:17], off offset:288 nt
	global_load_dwordx2 v[12:13], v[18:19], off nt
	global_load_dwordx2 v[14:15], v[18:19], off offset:32 nt
	global_load_dwordx2 v[26:27], v[18:19], off offset:256 nt
	global_load_dwordx2 v[24:25], v[18:19], off offset:288 nt
	v_or_b32_e32 v18, 32, v0
	v_or_b32_e32 v0, 48, v0
	v_ashrrev_i32_e32 v19, 31, v18
	v_ashrrev_i32_e32 v1, 31, v0
	v_lshlrev_b64 v[18:19], 12, v[18:19]
	v_lshlrev_b64 v[0:1], 12, v[0:1]
	s_mov_b32 s53, 0x80000
	v_lshl_add_u64 v[18:19], v[4:5], 0, v[18:19]
	v_lshl_add_u64 v[0:1], v[4:5], 0, v[0:1]
	v_add_co_u32_e32 v4, vcc, s53, v16
	s_mov_b64 s[4:5], 0x80000
	s_nop 0
	v_addc_co_u32_e32 v5, vcc, 0, v17, vcc
	s_mov_b32 s54, 0x90000
	global_load_dwordx2 v[28:29], v[18:19], off nt
	global_load_dwordx2 v[30:31], v[18:19], off offset:32 nt
	global_load_dwordx2 v[42:43], v[18:19], off offset:256 nt
	global_load_dwordx2 v[40:41], v[18:19], off offset:288 nt
	global_load_dwordx2 v[44:45], v[0:1], off nt
	global_load_dwordx2 v[46:47], v[0:1], off offset:32 nt
	global_load_dwordx2 v[58:59], v[0:1], off offset:256 nt
	global_load_dwordx2 v[62:63], v[0:1], off offset:288 nt
	v_lshl_add_u64 v[0:1], v[16:17], 0, s[4:5]
	global_load_dwordx2 v[66:67], v[4:5], off nt
	global_load_dwordx2 v[70:71], v[0:1], off offset:32 nt
	global_load_dwordx2 v[74:75], v[0:1], off offset:256 nt
	global_load_dwordx2 v[72:73], v[0:1], off offset:288 nt
	v_add_co_u32_e32 v4, vcc, s54, v16
	s_mov_b64 s[6:7], 0x90000
	s_nop 0
	v_addc_co_u32_e32 v5, vcc, 0, v17, vcc
	s_mov_b32 s55, 0xa0000
	v_lshl_add_u64 v[0:1], v[16:17], 0, s[6:7]
	global_load_dwordx2 v[76:77], v[4:5], off nt
	global_load_dwordx2 v[78:79], v[0:1], off offset:32 nt
	global_load_dwordx2 v[90:91], v[0:1], off offset:256 nt
	global_load_dwordx2 v[88:89], v[0:1], off offset:288 nt
	v_add_co_u32_e32 v4, vcc, s55, v16
	s_mov_b64 s[8:9], 0xa0000
	s_nop 0
	v_addc_co_u32_e32 v5, vcc, 0, v17, vcc
	s_mov_b32 s13, 0xb0000
	v_lshl_add_u64 v[0:1], v[16:17], 0, s[8:9]
	global_load_dwordx2 v[100:101], v[4:5], off nt
	global_load_dwordx2 v[102:103], v[0:1], off offset:32 nt
	global_load_dwordx2 v[106:107], v[0:1], off offset:256 nt
	global_load_dwordx2 v[104:105], v[0:1], off offset:288 nt
	v_add_co_u32_e32 v4, vcc, s13, v16
	s_ashr_i32 s37, s36, 31
	s_bfe_i64 s[12:13], s[12:13], 0x100000
	s_lshl_b64 s[24:25], s[36:37], 22
	s_lshl_b64 s[14:15], s[14:15], 23
	s_lshl_b64 s[12:13], s[12:13], 22
	s_add_u32 s42, s50, s12
	s_addc_u32 s43, s51, s13
	s_add_i32 s37, s52, 0x10000
	s_add_i32 s56, s52, 0x12000
	s_add_u32 s17, s22, s24
	s_addc_u32 s21, s23, s25
	s_mov_b64 s[10:11], 0xb0000
	v_addc_co_u32_e32 v5, vcc, 0, v17, vcc
	s_mov_b32 m0, s37
	s_add_u32 s12, s42, 0x200000
	v_lshl_add_u64 v[0:1], v[16:17], 0, s[10:11]
	global_load_dwordx2 v[108:109], v[4:5], off nt
	global_load_dwordx2 v[110:111], v[0:1], off offset:32 nt
	global_load_dwordx2 v[122:123], v[0:1], off offset:256 nt
	global_load_dwordx2 v[126:127], v[0:1], off offset:288 nt
	s_addc_u32 s13, s43, 0
	global_load_lds_dwordx4 v128, s[42:43]
	s_mov_b32 m0, s56
	s_add_i32 s57, s52, 0x14000
	s_add_i32 s58, s52, 0x16000
	global_load_lds_dwordx4 v130, s[42:43]
	s_mov_b32 m0, s57
	s_add_u32 s44, s17, s14
	global_load_lds_dwordx4 v128, s[12:13]
	s_mov_b32 m0, s58
	s_addc_u32 s45, s21, s15
	s_add_i32 s59, s52, 0x2000
	global_load_lds_dwordx4 v130, s[12:13]
	s_mov_b32 m0, s52
	s_add_u32 s12, s44, 0x200000
	global_load_lds_dwordx4 v128, s[44:45]
	s_mov_b32 m0, s59
	s_addc_u32 s13, s45, 0
	s_add_i32 s60, s52, 0x4000
	global_load_lds_dwordx4 v130, s[44:45]
	s_mov_b32 m0, s60
	s_add_i32 s61, s52, 0x6000
	global_load_lds_dwordx4 v128, s[12:13]
	s_mov_b32 m0, s61
	v_mov_b32_e32 v129, 0
	global_load_lds_dwordx4 v130, s[12:13]
	v_mov_b32_e32 v131, v129
	s_cmp_eq_u32 s16, 1
	s_mov_b32 s64, 0
	v_lshl_add_u64 v[118:119], s[42:43], 0, v[128:129]
	v_lshl_add_u64 v[116:117], s[42:43], 0, v[130:131]
	v_lshl_add_u64 v[112:113], s[44:45], 0, v[128:129]
	s_cselect_b64 s[12:13], -1, 0
	s_cmp_lg_u32 s16, 1
	v_lshl_add_u64 v[114:115], s[44:45], 0, v[130:131]
	s_cbranch_scc1 .LBB0_472
	s_barrier

.LBB0_485:
	v_lshl_add_u32 v150, s36, 8, v140
	v_lshl_or_b32 v152, s77, 8, v143
	v_and_b32_e32 v156, 1, v150
	v_and_b32_e32 v150, -2, v150
	v_lshl_add_u32 v152, v156, 4, v152
	s_mov_b32 s101, 0
	s_mov_b32 vcc_lo, 0x55555555
	s_mov_b32 vcc_hi, 0x55555555
	v_ashrrev_i32_e32 v151, 31, v150
	v_ashrrev_i32_e32 v153, 31, v152
	v_lshlrev_b64 v[154:155], 13, v[150:151]
	v_lshl_add_u64 v[154:155], s[14:15], 0, v[154:155]
	v_lshlrev_b64 v[152:153], 2, v[152:153]
	v_lshl_add_u64 v[154:155], v[154:155], 0, v[152:153]
	s_mov_b32 s100, 0x0
	v_lshl_add_u64 v[158:159], v[154:155], 0, s[100:101]
	s_mov_b32 s100, 0x2000
	v_lshl_add_u64 v[160:161], v[154:155], 0, s[100:101]
	v_cndmask_b32_dpp v184, v4, v0, vcc quad_perm:[0,0,2,2] row_mask:0xf bank_mask:0xf
	v_cndmask_b32_dpp v185, v5, v1, vcc quad_perm:[0,0,2,2] row_mask:0xf bank_mask:0xf
	v_cndmask_b32_dpp v186, v6, v2, vcc quad_perm:[0,0,2,2] row_mask:0xf bank_mask:0xf
	v_cndmask_b32_dpp v187, v7, v3, vcc quad_perm:[0,0,2,2] row_mask:0xf bank_mask:0xf
	v_cndmask_b32_dpp v188, v20, v16, vcc quad_perm:[0,0,2,2] row_mask:0xf bank_mask:0xf
	v_cndmask_b32_dpp v189, v21, v17, vcc quad_perm:[0,0,2,2] row_mask:0xf bank_mask:0xf
	v_cndmask_b32_dpp v190, v22, v18, vcc quad_perm:[0,0,2,2] row_mask:0xf bank_mask:0xf
	v_cndmask_b32_dpp v191, v23, v19, vcc quad_perm:[0,0,2,2] row_mask:0xf bank_mask:0xf
	s_not_b64 vcc, vcc
	v_cndmask_b32_dpp v4, v0, v4, vcc quad_perm:[1,1,3,3] row_mask:0xf bank_mask:0xf
	v_cndmask_b32_dpp v5, v1, v5, vcc quad_perm:[1,1,3,3] row_mask:0xf bank_mask:0xf
	v_cndmask_b32_dpp v6, v2, v6, vcc quad_perm:[1,1,3,3] row_mask:0xf bank_mask:0xf
	v_cndmask_b32_dpp v7, v3, v7, vcc quad_perm:[1,1,3,3] row_mask:0xf bank_mask:0xf
	v_cndmask_b32_dpp v20, v16, v20, vcc quad_perm:[1,1,3,3] row_mask:0xf bank_mask:0xf
	v_cndmask_b32_dpp v21, v17, v21, vcc quad_perm:[1,1,3,3] row_mask:0xf bank_mask:0xf
	v_cndmask_b32_dpp v22, v18, v22, vcc quad_perm:[1,1,3,3] row_mask:0xf bank_mask:0xf
	v_cndmask_b32_dpp v23, v19, v23, vcc quad_perm:[1,1,3,3] row_mask:0xf bank_mask:0xf
	s_not_b64 vcc, vcc
	global_store_dwordx4 v[158:159], v[184:187], off nt
	global_store_dwordx4 v[158:159], v[188:191], off offset:512 nt
	global_store_dwordx4 v[160:161], v[4:7], off nt
	global_store_dwordx4 v[160:161], v[20:23], off offset:512 nt
	s_mov_b32 s100, 0x20000
	v_lshl_add_u64 v[158:159], v[154:155], 0, s[100:101]
	s_mov_b32 s100, 0x22000
	v_lshl_add_u64 v[160:161], v[154:155], 0, s[100:101]
	v_cndmask_b32_dpp v192, v12, v8, vcc quad_perm:[0,0,2,2] row_mask:0xf bank_mask:0xf
	v_cndmask_b32_dpp v193, v13, v9, vcc quad_perm:[0,0,2,2] row_mask:0xf bank_mask:0xf
	v_cndmask_b32_dpp v194, v14, v10, vcc quad_perm:[0,0,2,2] row_mask:0xf bank_mask:0xf
	v_cndmask_b32_dpp v195, v15, v11, vcc quad_perm:[0,0,2,2] row_mask:0xf bank_mask:0xf
	v_cndmask_b32_dpp v196, v36, v32, vcc quad_perm:[0,0,2,2] row_mask:0xf bank_mask:0xf
	v_cndmask_b32_dpp v197, v37, v33, vcc quad_perm:[0,0,2,2] row_mask:0xf bank_mask:0xf
	v_cndmask_b32_dpp v198, v38, v34, vcc quad_perm:[0,0,2,2] row_mask:0xf bank_mask:0xf
	v_cndmask_b32_dpp v199, v39, v35, vcc quad_perm:[0,0,2,2] row_mask:0xf bank_mask:0xf
	s_not_b64 vcc, vcc
	v_cndmask_b32_dpp v12, v8, v12, vcc quad_perm:[1,1,3,3] row_mask:0xf bank_mask:0xf
	v_cndmask_b32_dpp v13, v9, v13, vcc quad_perm:[1,1,3,3] row_mask:0xf bank_mask:0xf
	v_cndmask_b32_dpp v14, v10, v14, vcc quad_perm:[1,1,3,3] row_mask:0xf bank_mask:0xf
	v_cndmask_b32_dpp v15, v11, v15, vcc quad_perm:[1,1,3,3] row_mask:0xf bank_mask:0xf
	v_cndmask_b32_dpp v36, v32, v36, vcc quad_perm:[1,1,3,3] row_mask:0xf bank_mask:0xf
	v_cndmask_b32_dpp v37, v33, v37, vcc quad_perm:[1,1,3,3] row_mask:0xf bank_mask:0xf
	v_cndmask_b32_dpp v38, v34, v38, vcc quad_perm:[1,1,3,3] row_mask:0xf bank_mask:0xf
	v_cndmask_b32_dpp v39, v35, v39, vcc quad_perm:[1,1,3,3] row_mask:0xf bank_mask:0xf
	s_not_b64 vcc, vcc
	global_store_dwordx4 v[158:159], v[192:195], off nt
	global_store_dwordx4 v[158:159], v[196:199], off offset:512 nt
	global_store_dwordx4 v[160:161], v[12:15], off nt
	global_store_dwordx4 v[160:161], v[36:39], off offset:512 nt
	s_mov_b32 s100, 0x40000
	v_lshl_add_u64 v[158:159], v[154:155], 0, s[100:101]
	s_mov_b32 s100, 0x42000
	v_lshl_add_u64 v[160:161], v[154:155], 0, s[100:101]
	v_cndmask_b32_dpp v184, v28, v24, vcc quad_perm:[0,0,2,2] row_mask:0xf bank_mask:0xf
	v_cndmask_b32_dpp v185, v29, v25, vcc quad_perm:[0,0,2,2] row_mask:0xf bank_mask:0xf
	v_cndmask_b32_dpp v186, v30, v26, vcc quad_perm:[0,0,2,2] row_mask:0xf bank_mask:0xf
	v_cndmask_b32_dpp v187, v31, v27, vcc quad_perm:[0,0,2,2] row_mask:0xf bank_mask:0xf
	v_cndmask_b32_dpp v188, v52, v48, vcc quad_perm:[0,0,2,2] row_mask:0xf bank_mask:0xf
	v_cndmask_b32_dpp v189, v53, v49, vcc quad_perm:[0,0,2,2] row_mask:0xf bank_mask:0xf
	v_cndmask_b32_dpp v190, v54, v50, vcc quad_perm:[0,0,2,2] row_mask:0xf bank_mask:0xf
	v_cndmask_b32_dpp v191, v55, v51, vcc quad_perm:[0,0,2,2] row_mask:0xf bank_mask:0xf
	s_not_b64 vcc, vcc
	v_cndmask_b32_dpp v28, v24, v28, vcc quad_perm:[1,1,3,3] row_mask:0xf bank_mask:0xf
	v_cndmask_b32_dpp v29, v25, v29, vcc quad_perm:[1,1,3,3] row_mask:0xf bank_mask:0xf
	v_cndmask_b32_dpp v30, v26, v30, vcc quad_perm:[1,1,3,3] row_mask:0xf bank_mask:0xf
	v_cndmask_b32_dpp v31, v27, v31, vcc quad_perm:[1,1,3,3] row_mask:0xf bank_mask:0xf
	v_cndmask_b32_dpp v52, v48, v52, vcc quad_perm:[1,1,3,3] row_mask:0xf bank_mask:0xf
	v_cndmask_b32_dpp v53, v49, v53, vcc quad_perm:[1,1,3,3] row_mask:0xf bank_mask:0xf
	v_cndmask_b32_dpp v54, v50, v54, vcc quad_perm:[1,1,3,3] row_mask:0xf bank_mask:0xf
	v_cndmask_b32_dpp v55, v51, v55, vcc quad_perm:[1,1,3,3] row_mask:0xf bank_mask:0xf
	s_not_b64 vcc, vcc
	global_store_dwordx4 v[158:159], v[184:187], off nt
	global_store_dwordx4 v[158:159], v[188:191], off offset:512 nt
	global_store_dwordx4 v[160:161], v[28:31], off nt
	global_store_dwordx4 v[160:161], v[52:55], off offset:512 nt
	s_mov_b32 s100, 0x60000
	v_lshl_add_u64 v[158:159], v[154:155], 0, s[100:101]
	s_mov_b32 s100, 0x62000
	v_lshl_add_u64 v[160:161], v[154:155], 0, s[100:101]
	v_cndmask_b32_dpp v192, v44, v40, vcc quad_perm:[0,0,2,2] row_mask:0xf bank_mask:0xf
	v_cndmask_b32_dpp v193, v45, v41, vcc quad_perm:[0,0,2,2] row_mask:0xf bank_mask:0xf
	v_cndmask_b32_dpp v194, v46, v42, vcc quad_perm:[0,0,2,2] row_mask:0xf bank_mask:0xf
	v_cndmask_b32_dpp v195, v47, v43, vcc quad_perm:[0,0,2,2] row_mask:0xf bank_mask:0xf
	v_cndmask_b32_dpp v196, v60, v56, vcc quad_perm:[0,0,2,2] row_mask:0xf bank_mask:0xf
	v_cndmask_b32_dpp v197, v61, v57, vcc quad_perm:[0,0,2,2] row_mask:0xf bank_mask:0xf
	v_cndmask_b32_dpp v198, v62, v58, vcc quad_perm:[0,0,2,2] row_mask:0xf bank_mask:0xf
	v_cndmask_b32_dpp v199, v63, v59, vcc quad_perm:[0,0,2,2] row_mask:0xf bank_mask:0xf
	s_not_b64 vcc, vcc
	v_cndmask_b32_dpp v44, v40, v44, vcc quad_perm:[1,1,3,3] row_mask:0xf bank_mask:0xf
	v_cndmask_b32_dpp v45, v41, v45, vcc quad_perm:[1,1,3,3] row_mask:0xf bank_mask:0xf
	v_cndmask_b32_dpp v46, v42, v46, vcc quad_perm:[1,1,3,3] row_mask:0xf bank_mask:0xf
	v_cndmask_b32_dpp v47, v43, v47, vcc quad_perm:[1,1,3,3] row_mask:0xf bank_mask:0xf
	v_cndmask_b32_dpp v60, v56, v60, vcc quad_perm:[1,1,3,3] row_mask:0xf bank_mask:0xf
	v_cndmask_b32_dpp v61, v57, v61, vcc quad_perm:[1,1,3,3] row_mask:0xf bank_mask:0xf
	v_cndmask_b32_dpp v62, v58, v62, vcc quad_perm:[1,1,3,3] row_mask:0xf bank_mask:0xf
	v_cndmask_b32_dpp v63, v59, v63, vcc quad_perm:[1,1,3,3] row_mask:0xf bank_mask:0xf
	s_not_b64 vcc, vcc
	global_store_dwordx4 v[158:159], v[192:195], off nt
	global_store_dwordx4 v[158:159], v[196:199], off offset:512 nt
	global_store_dwordx4 v[160:161], v[44:47], off nt
	global_store_dwordx4 v[160:161], v[60:63], off offset:512 nt
	s_mov_b32 s100, 0x100000
	v_lshl_add_u64 v[158:159], v[154:155], 0, s[100:101]
	s_mov_b32 s100, 0x102000
	v_lshl_add_u64 v[160:161], v[154:155], 0, s[100:101]
	v_cndmask_b32_dpp v184, v68, v64, vcc quad_perm:[0,0,2,2] row_mask:0xf bank_mask:0xf
	v_cndmask_b32_dpp v185, v69, v65, vcc quad_perm:[0,0,2,2] row_mask:0xf bank_mask:0xf
	v_cndmask_b32_dpp v186, v70, v66, vcc quad_perm:[0,0,2,2] row_mask:0xf bank_mask:0xf
	v_cndmask_b32_dpp v187, v71, v67, vcc quad_perm:[0,0,2,2] row_mask:0xf bank_mask:0xf
	v_cndmask_b32_dpp v188, v84, v80, vcc quad_perm:[0,0,2,2] row_mask:0xf bank_mask:0xf
	v_cndmask_b32_dpp v189, v85, v81, vcc quad_perm:[0,0,2,2] row_mask:0xf bank_mask:0xf
	v_cndmask_b32_dpp v190, v86, v82, vcc quad_perm:[0,0,2,2] row_mask:0xf bank_mask:0xf
	v_cndmask_b32_dpp v191, v87, v83, vcc quad_perm:[0,0,2,2] row_mask:0xf bank_mask:0xf
	s_not_b64 vcc, vcc
	v_cndmask_b32_dpp v68, v64, v68, vcc quad_perm:[1,1,3,3] row_mask:0xf bank_mask:0xf
	v_cndmask_b32_dpp v69, v65, v69, vcc quad_perm:[1,1,3,3] row_mask:0xf bank_mask:0xf
	v_cndmask_b32_dpp v70, v66, v70, vcc quad_perm:[1,1,3,3] row_mask:0xf bank_mask:0xf
	v_cndmask_b32_dpp v71, v67, v71, vcc quad_perm:[1,1,3,3] row_mask:0xf bank_mask:0xf
	v_cndmask_b32_dpp v84, v80, v84, vcc quad_perm:[1,1,3,3] row_mask:0xf bank_mask:0xf
	v_cndmask_b32_dpp v85, v81, v85, vcc quad_perm:[1,1,3,3] row_mask:0xf bank_mask:0xf
	v_cndmask_b32_dpp v86, v82, v86, vcc quad_perm:[1,1,3,3] row_mask:0xf bank_mask:0xf
	v_cndmask_b32_dpp v87, v83, v87, vcc quad_perm:[1,1,3,3] row_mask:0xf bank_mask:0xf
	s_not_b64 vcc, vcc
	global_store_dwordx4 v[158:159], v[184:187], off nt
	global_store_dwordx4 v[158:159], v[188:191], off offset:512 nt
	global_store_dwordx4 v[160:161], v[68:71], off nt
	global_store_dwordx4 v[160:161], v[84:87], off offset:512 nt
	s_mov_b32 s100, 0x120000
	v_lshl_add_u64 v[158:159], v[154:155], 0, s[100:101]
	s_mov_b32 s100, 0x122000
	v_lshl_add_u64 v[160:161], v[154:155], 0, s[100:101]
	v_cndmask_b32_dpp v192, v76, v72, vcc quad_perm:[0,0,2,2] row_mask:0xf bank_mask:0xf
	v_cndmask_b32_dpp v193, v77, v73, vcc quad_perm:[0,0,2,2] row_mask:0xf bank_mask:0xf
	v_cndmask_b32_dpp v194, v78, v74, vcc quad_perm:[0,0,2,2] row_mask:0xf bank_mask:0xf
	v_cndmask_b32_dpp v195, v79, v75, vcc quad_perm:[0,0,2,2] row_mask:0xf bank_mask:0xf
	v_cndmask_b32_dpp v196, v96, v92, vcc quad_perm:[0,0,2,2] row_mask:0xf bank_mask:0xf
	v_cndmask_b32_dpp v197, v97, v93, vcc quad_perm:[0,0,2,2] row_mask:0xf bank_mask:0xf
	v_cndmask_b32_dpp v198, v98, v94, vcc quad_perm:[0,0,2,2] row_mask:0xf bank_mask:0xf
	v_cndmask_b32_dpp v199, v99, v95, vcc quad_perm:[0,0,2,2] row_mask:0xf bank_mask:0xf
	s_not_b64 vcc, vcc
	v_cndmask_b32_dpp v76, v72, v76, vcc quad_perm:[1,1,3,3] row_mask:0xf bank_mask:0xf
	v_cndmask_b32_dpp v77, v73, v77, vcc quad_perm:[1,1,3,3] row_mask:0xf bank_mask:0xf
	v_cndmask_b32_dpp v78, v74, v78, vcc quad_perm:[1,1,3,3] row_mask:0xf bank_mask:0xf
	v_cndmask_b32_dpp v79, v75, v79, vcc quad_perm:[1,1,3,3] row_mask:0xf bank_mask:0xf
	v_cndmask_b32_dpp v96, v92, v96, vcc quad_perm:[1,1,3,3] row_mask:0xf bank_mask:0xf
	v_cndmask_b32_dpp v97, v93, v97, vcc quad_perm:[1,1,3,3] row_mask:0xf bank_mask:0xf
	v_cndmask_b32_dpp v98, v94, v98, vcc quad_perm:[1,1,3,3] row_mask:0xf bank_mask:0xf
	v_cndmask_b32_dpp v99, v95, v99, vcc quad_perm:[1,1,3,3] row_mask:0xf bank_mask:0xf
	s_not_b64 vcc, vcc
	global_store_dwordx4 v[158:159], v[192:195], off nt
	global_store_dwordx4 v[158:159], v[196:199], off offset:512 nt
	global_store_dwordx4 v[160:161], v[76:79], off nt
	global_store_dwordx4 v[160:161], v[96:99], off offset:512 nt
	s_mov_b32 s100, 0x140000
	v_lshl_add_u64 v[158:159], v[154:155], 0, s[100:101]
	s_mov_b32 s100, 0x142000
	v_lshl_add_u64 v[160:161], v[154:155], 0, s[100:101]
	v_cndmask_b32_dpp v184, v100, v88, vcc quad_perm:[0,0,2,2] row_mask:0xf bank_mask:0xf
	v_cndmask_b32_dpp v185, v101, v89, vcc quad_perm:[0,0,2,2] row_mask:0xf bank_mask:0xf
	v_cndmask_b32_dpp v186, v102, v90, vcc quad_perm:[0,0,2,2] row_mask:0xf bank_mask:0xf
	v_cndmask_b32_dpp v187, v103, v91, vcc quad_perm:[0,0,2,2] row_mask:0xf bank_mask:0xf
	v_cndmask_b32_dpp v188, v116, v112, vcc quad_perm:[0,0,2,2] row_mask:0xf bank_mask:0xf
	v_cndmask_b32_dpp v189, v117, v113, vcc quad_perm:[0,0,2,2] row_mask:0xf bank_mask:0xf
	v_cndmask_b32_dpp v190, v118, v114, vcc quad_perm:[0,0,2,2] row_mask:0xf bank_mask:0xf
	v_cndmask_b32_dpp v191, v119, v115, vcc quad_perm:[0,0,2,2] row_mask:0xf bank_mask:0xf
	s_not_b64 vcc, vcc
	v_cndmask_b32_dpp v100, v88, v100, vcc quad_perm:[1,1,3,3] row_mask:0xf bank_mask:0xf
	v_cndmask_b32_dpp v101, v89, v101, vcc quad_perm:[1,1,3,3] row_mask:0xf bank_mask:0xf
	v_cndmask_b32_dpp v102, v90, v102, vcc quad_perm:[1,1,3,3] row_mask:0xf bank_mask:0xf
	v_cndmask_b32_dpp v103, v91, v103, vcc quad_perm:[1,1,3,3] row_mask:0xf bank_mask:0xf
	v_cndmask_b32_dpp v116, v112, v116, vcc quad_perm:[1,1,3,3] row_mask:0xf bank_mask:0xf
	v_cndmask_b32_dpp v117, v113, v117, vcc quad_perm:[1,1,3,3] row_mask:0xf bank_mask:0xf
	v_cndmask_b32_dpp v118, v114, v118, vcc quad_perm:[1,1,3,3] row_mask:0xf bank_mask:0xf
	v_cndmask_b32_dpp v119, v115, v119, vcc quad_perm:[1,1,3,3] row_mask:0xf bank_mask:0xf
	s_not_b64 vcc, vcc
	global_store_dwordx4 v[158:159], v[184:187], off nt
	global_store_dwordx4 v[158:159], v[188:191], off offset:512 nt
	global_store_dwordx4 v[160:161], v[100:103], off nt
	global_store_dwordx4 v[160:161], v[116:119], off offset:512 nt
	s_mov_b32 s100, 0x160000
	v_lshl_add_u64 v[158:159], v[154:155], 0, s[100:101]
	s_mov_b32 s100, 0x162000
	v_lshl_add_u64 v[160:161], v[154:155], 0, s[100:101]
	v_cndmask_b32_dpp v192, v108, v104, vcc quad_perm:[0,0,2,2] row_mask:0xf bank_mask:0xf
	v_cndmask_b32_dpp v193, v109, v105, vcc quad_perm:[0,0,2,2] row_mask:0xf bank_mask:0xf
	v_cndmask_b32_dpp v194, v110, v106, vcc quad_perm:[0,0,2,2] row_mask:0xf bank_mask:0xf
	v_cndmask_b32_dpp v195, v111, v107, vcc quad_perm:[0,0,2,2] row_mask:0xf bank_mask:0xf
	v_cndmask_b32_dpp v196, v124, v120, vcc quad_perm:[0,0,2,2] row_mask:0xf bank_mask:0xf
	v_cndmask_b32_dpp v197, v125, v121, vcc quad_perm:[0,0,2,2] row_mask:0xf bank_mask:0xf
	v_cndmask_b32_dpp v198, v126, v122, vcc quad_perm:[0,0,2,2] row_mask:0xf bank_mask:0xf
	v_cndmask_b32_dpp v199, v127, v123, vcc quad_perm:[0,0,2,2] row_mask:0xf bank_mask:0xf
	s_not_b64 vcc, vcc
	v_cndmask_b32_dpp v108, v104, v108, vcc quad_perm:[1,1,3,3] row_mask:0xf bank_mask:0xf
	v_cndmask_b32_dpp v109, v105, v109, vcc quad_perm:[1,1,3,3] row_mask:0xf bank_mask:0xf
	v_cndmask_b32_dpp v110, v106, v110, vcc quad_perm:[1,1,3,3] row_mask:0xf bank_mask:0xf
	v_cndmask_b32_dpp v111, v107, v111, vcc quad_perm:[1,1,3,3] row_mask:0xf bank_mask:0xf
	v_cndmask_b32_dpp v124, v120, v124, vcc quad_perm:[1,1,3,3] row_mask:0xf bank_mask:0xf
	v_cndmask_b32_dpp v125, v121, v125, vcc quad_perm:[1,1,3,3] row_mask:0xf bank_mask:0xf
	v_cndmask_b32_dpp v126, v122, v126, vcc quad_perm:[1,1,3,3] row_mask:0xf bank_mask:0xf
	v_cndmask_b32_dpp v127, v123, v127, vcc quad_perm:[1,1,3,3] row_mask:0xf bank_mask:0xf
	s_not_b64 vcc, vcc
	global_store_dwordx4 v[158:159], v[192:195], off nt
	global_store_dwordx4 v[158:159], v[196:199], off offset:512 nt
	global_store_dwordx4 v[160:161], v[108:111], off nt
	global_store_dwordx4 v[160:161], v[124:127], off offset:512 nt
	s_andn2_b64 vcc, exec, s[0:1]
	s_mov_b64 s[0:1], -1
	s_cbranch_vccnz .LBB0_474
	v_lshl_add_u32 v0, s34, 8, v140
	s_lshl_b64 s[0:1], s[46:47], 25
	v_lshl_or_b32 v2, s30, 8, v143
	s_add_u32 s0, s62, s0
	v_or_b32_e32 v12, 16, v0
	s_addc_u32 s1, s63, s1
	v_ashrrev_i32_e32 v3, 31, v2
	v_ashrrev_i32_e32 v1, 31, v0
	v_ashrrev_i32_e32 v13, 31, v12
	v_lshl_add_u64 v[4:5], v[2:3], 1, s[0:1]
	v_lshlrev_b64 v[2:3], 12, v[0:1]
	v_lshlrev_b64 v[12:13], 12, v[12:13]
	v_lshl_add_u64 v[16:17], v[4:5], 0, v[2:3]
	v_lshl_add_u64 v[18:19], v[4:5], 0, v[12:13]
	global_load_dwordx2 v[2:3], v[16:17], off nt
	global_load_dwordx2 v[6:7], v[16:17], off offset:32 nt
	global_load_dwordx2 v[10:11], v[16:17], off offset:256 nt
	global_load_dwordx2 v[8:9], v[16:17], off offset:288 nt
	global_load_dwordx2 v[12:13], v[18:19], off nt
	global_load_dwordx2 v[14:15], v[18:19], off offset:32 nt
	global_load_dwordx2 v[26:27], v[18:19], off offset:256 nt
	global_load_dwordx2 v[24:25], v[18:19], off offset:288 nt
	v_or_b32_e32 v18, 32, v0
	v_or_b32_e32 v0, 48, v0
	v_ashrrev_i32_e32 v19, 31, v18
	v_ashrrev_i32_e32 v1, 31, v0
	v_lshlrev_b64 v[18:19], 12, v[18:19]
	v_lshlrev_b64 v[0:1], 12, v[0:1]
	v_lshl_add_u64 v[18:19], v[4:5], 0, v[18:19]
	v_lshl_add_u64 v[0:1], v[4:5], 0, v[0:1]
	v_add_co_u32_e32 v4, vcc, s53, v16
	global_load_dwordx2 v[28:29], v[18:19], off nt
	global_load_dwordx2 v[30:31], v[18:19], off offset:32 nt
	global_load_dwordx2 v[42:43], v[18:19], off offset:256 nt
	global_load_dwordx2 v[40:41], v[18:19], off offset:288 nt
	v_addc_co_u32_e32 v5, vcc, 0, v17, vcc
	global_load_dwordx2 v[44:45], v[0:1], off nt
	global_load_dwordx2 v[46:47], v[0:1], off offset:32 nt
	global_load_dwordx2 v[58:59], v[0:1], off offset:256 nt
	global_load_dwordx2 v[62:63], v[0:1], off offset:288 nt
	v_lshl_add_u64 v[0:1], v[16:17], 0, s[4:5]
	global_load_dwordx2 v[66:67], v[4:5], off nt
	global_load_dwordx2 v[70:71], v[0:1], off offset:32 nt
	global_load_dwordx2 v[76:77], v[0:1], off offset:256 nt
	global_load_dwordx2 v[72:73], v[0:1], off offset:288 nt
	v_add_co_u32_e32 v4, vcc, s54, v16
	v_lshl_add_u64 v[0:1], v[16:17], 0, s[6:7]
	s_nop 0
	v_addc_co_u32_e32 v5, vcc, 0, v17, vcc
	global_load_dwordx2 v[74:75], v[4:5], off nt
	global_load_dwordx2 v[78:79], v[0:1], off offset:32 nt
	global_load_dwordx2 v[90:91], v[0:1], off offset:256 nt
	global_load_dwordx2 v[88:89], v[0:1], off offset:288 nt
	v_add_co_u32_e32 v4, vcc, s55, v16
	v_lshl_add_u64 v[0:1], v[16:17], 0, s[8:9]
	s_nop 0
	v_addc_co_u32_e32 v5, vcc, 0, v17, vcc
	global_load_dwordx2 v[100:101], v[4:5], off nt
	global_load_dwordx2 v[102:103], v[0:1], off offset:32 nt
	global_load_dwordx2 v[106:107], v[0:1], off offset:256 nt
	global_load_dwordx2 v[104:105], v[0:1], off offset:288 nt
	v_add_co_u32_e32 v4, vcc, 0xb0000, v16
	v_lshl_add_u64 v[0:1], v[16:17], 0, s[10:11]
	s_nop 0
	v_addc_co_u32_e32 v5, vcc, 0, v17, vcc
	global_load_dwordx2 v[108:109], v[4:5], off nt
	global_load_dwordx2 v[110:111], v[0:1], off offset:32 nt
	global_load_dwordx2 v[122:123], v[0:1], off offset:256 nt
	global_load_dwordx2 v[126:127], v[0:1], off offset:288 nt
	s_andn2_b64 vcc, exec, s[12:13]
	s_cbranch_vccnz .LBB0_473
	s_barrier
	s_branch .LBB0_473
